# loop-edge rotation on both GEMM K-loops (lever 9): counter / pointer increments / exit compare issued behind the last MFMA block, in front of the closing barrier; only the branch stays behind the barr
# baseline (speedup 1.0000x reference)
.LBB0_109:
	s_add_u32 s16, s40, 0xfff80080
	s_addc_u32 s17, s41, -1
	s_add_i32 s82, 0, 0x10000
	s_cmp_eq_u32 s80, 28
	s_cselect_b32 s19, s11, s17
	s_cselect_b32 s18, s76, s16
	s_cselect_b32 s17, s9, s53
	s_cselect_b32 s16, s78, s52
	s_add_i32 s84, 0, 0x14000
	v_add_u32_e32 v108, s82, v161
	v_add_u32_e32 v158, s84, v161
	ds_read_b128 v[96:99], v108
	ds_read_b128 v[100:103], v108 offset:1024
	ds_read_b128 v[104:107], v108 offset:2048
	ds_read_b128 v[108:111], v108 offset:3072
	ds_read_b128 v[154:157], v158
	ds_read_b128 v[164:167], v158 offset:1024
	ds_read_b128 v[168:171], v158 offset:2048
	ds_read_b128 v[172:175], v158 offset:3072
	v_lshl_add_u64 v[158:159], s[40:41], 0, v[150:151]
	s_add_i32 m0, s26, 0xc000
	ds_read_b128 v[176:179], v163
	ds_read_b128 v[180:183], v163 offset:1024
	ds_read_b128 v[184:187], v163 offset:2048
	ds_read_b128 v[188:191], v163 offset:3072
	ds_read_b128 v[202:205], v163 offset:4096
	ds_read_b128 v[206:209], v163 offset:5120
	ds_read_b128 v[210:213], v163 offset:6144
	ds_read_b128 v[214:217], v163 offset:7168
	global_load_lds_dwordx4 v[158:159], off
	v_lshl_add_u64 v[158:159], s[40:41], 0, v[152:153]
	s_add_i32 m0, s26, 0xe000
	s_nop 0
	global_load_lds_dwordx4 v[158:159], off
	s_waitcnt vmcnt(8)
	s_waitcnt lgkmcnt(0)
	s_barrier
	s_setprio 1
	s_waitcnt lgkmcnt(0)
	v_mfma_f32_16x16x32_bf16 v[140:143], v[96:99], v[176:179], v[140:143]
	v_mfma_f32_16x16x32_bf16 v[136:139], v[104:107], v[176:179], v[136:139]
	v_mfma_f32_16x16x32_bf16 v[124:127], v[96:99], v[184:187], v[124:127]
	v_mfma_f32_16x16x32_bf16 v[120:123], v[104:107], v[184:187], v[120:123]
	v_mfma_f32_16x16x32_bf16 v[92:95], v[96:99], v[202:205], v[92:95]
	v_mfma_f32_16x16x32_bf16 v[88:91], v[104:107], v[202:205], v[88:91]
	v_mfma_f32_16x16x32_bf16 v[76:79], v[96:99], v[210:213], v[76:79]
	v_mfma_f32_16x16x32_bf16 v[72:75], v[104:107], v[210:213], v[72:75]
	v_mfma_f32_16x16x32_bf16 v[140:143], v[100:103], v[180:183], v[140:143]
	v_mfma_f32_16x16x32_bf16 v[136:139], v[108:111], v[180:183], v[136:139]
	v_mfma_f32_16x16x32_bf16 v[124:127], v[100:103], v[188:191], v[124:127]
	v_mfma_f32_16x16x32_bf16 v[120:123], v[108:111], v[188:191], v[120:123]
	v_mfma_f32_16x16x32_bf16 v[92:95], v[100:103], v[206:209], v[92:95]
	v_mfma_f32_16x16x32_bf16 v[88:91], v[108:111], v[206:209], v[88:91]
	v_mfma_f32_16x16x32_bf16 v[76:79], v[100:103], v[214:217], v[76:79]
	v_mfma_f32_16x16x32_bf16 v[72:75], v[108:111], v[214:217], v[72:75]
	s_setprio 0
	s_setprio 1
	v_mfma_f32_16x16x32_bf16 v[132:135], v[154:157], v[176:179], v[132:135]
	v_mfma_f32_16x16x32_bf16 v[128:131], v[168:171], v[176:179], v[128:131]
	v_mfma_f32_16x16x32_bf16 v[116:119], v[154:157], v[184:187], v[116:119]
	v_mfma_f32_16x16x32_bf16 v[112:115], v[168:171], v[184:187], v[112:115]
	v_mfma_f32_16x16x32_bf16 v[84:87], v[154:157], v[202:205], v[84:87]
	v_mfma_f32_16x16x32_bf16 v[80:83], v[168:171], v[202:205], v[80:83]
	v_mfma_f32_16x16x32_bf16 v[68:71], v[154:157], v[210:213], v[68:71]
	v_mfma_f32_16x16x32_bf16 v[64:67], v[168:171], v[210:213], v[64:67]
	v_mfma_f32_16x16x32_bf16 v[132:135], v[164:167], v[180:183], v[132:135]
	v_mfma_f32_16x16x32_bf16 v[128:131], v[172:175], v[180:183], v[128:131]
	v_mfma_f32_16x16x32_bf16 v[116:119], v[164:167], v[188:191], v[116:119]
	v_mfma_f32_16x16x32_bf16 v[112:115], v[172:175], v[188:191], v[112:115]
	v_mfma_f32_16x16x32_bf16 v[84:87], v[164:167], v[206:209], v[84:87]
	v_mfma_f32_16x16x32_bf16 v[80:83], v[172:175], v[206:209], v[80:83]
	v_mfma_f32_16x16x32_bf16 v[68:71], v[164:167], v[214:217], v[68:71]
	v_mfma_f32_16x16x32_bf16 v[64:67], v[172:175], v[214:217], v[64:67]
	s_setprio 0
	s_barrier
	s_add_i32 s82, s82, s24
	v_lshl_add_u64 v[158:159], s[16:17], 0, v[192:193]
	s_mov_b32 m0, s82
	ds_read_b128 v[176:179], v163 offset:16384
	ds_read_b128 v[180:183], v163 offset:17408
	ds_read_b128 v[184:187], v163 offset:18432
	ds_read_b128 v[188:191], v163 offset:19456
	ds_read_b128 v[202:205], v163 offset:20480
	ds_read_b128 v[206:209], v163 offset:21504
	ds_read_b128 v[210:213], v163 offset:22528
	ds_read_b128 v[214:217], v163 offset:23552
	global_load_lds_dwordx4 v[158:159], off
	s_add_i32 m0, s82, 0x2000
	s_add_u32 vcc_lo, s16, 0x80000
	v_lshl_add_u64 v[196:197], s[16:17], 0, v[144:145]
	s_addc_u32 vcc_hi, s17, 0
	s_add_i32 s82, s84, s24
	global_load_lds_dwordx4 v[196:197], off
	v_lshl_add_u64 v[218:219], vcc, 0, v[192:193]
	s_mov_b32 m0, s82
	v_lshl_add_u64 v[220:221], s[18:19], 0, v[146:147]
	global_load_lds_dwordx4 v[218:219], off
	v_lshl_add_u64 v[218:219], vcc, 0, v[144:145]
	s_add_i32 m0, s82, 0x2000
	s_nop 0
	global_load_lds_dwordx4 v[218:219], off
	v_lshl_add_u64 v[218:219], s[18:19], 0, v[148:149]
	s_mov_b32 m0, s26
	s_nop 0
	global_load_lds_dwordx4 v[218:219], off
	s_mov_b32 m0, s28
	s_nop 0
	global_load_lds_dwordx4 v[220:221], off
	s_waitcnt vmcnt(8)
	s_waitcnt lgkmcnt(0)
	s_barrier
	s_setprio 1
	s_waitcnt lgkmcnt(0)
	v_mfma_f32_16x16x32_bf16 v[60:63], v[96:99], v[176:179], v[60:63]
	v_mfma_f32_16x16x32_bf16 v[56:59], v[104:107], v[176:179], v[56:59]
	v_mfma_f32_16x16x32_bf16 v[48:51], v[96:99], v[184:187], v[48:51]
	v_mfma_f32_16x16x32_bf16 v[40:43], v[104:107], v[184:187], v[40:43]
	v_mfma_f32_16x16x32_bf16 v[32:35], v[96:99], v[202:205], v[32:35]
	v_mfma_f32_16x16x32_bf16 v[24:27], v[104:107], v[202:205], v[24:27]
	v_mfma_f32_16x16x32_bf16 v[16:19], v[96:99], v[210:213], v[16:19]
	v_mfma_f32_16x16x32_bf16 v[8:11], v[104:107], v[210:213], v[8:11]
	v_mfma_f32_16x16x32_bf16 v[60:63], v[100:103], v[180:183], v[60:63]
	v_mfma_f32_16x16x32_bf16 v[56:59], v[108:111], v[180:183], v[56:59]
	v_mfma_f32_16x16x32_bf16 v[48:51], v[100:103], v[188:191], v[48:51]
	v_mfma_f32_16x16x32_bf16 v[40:43], v[108:111], v[188:191], v[40:43]
	v_mfma_f32_16x16x32_bf16 v[32:35], v[100:103], v[206:209], v[32:35]
	v_mfma_f32_16x16x32_bf16 v[24:27], v[108:111], v[206:209], v[24:27]
	v_mfma_f32_16x16x32_bf16 v[16:19], v[100:103], v[214:217], v[16:19]
	v_mfma_f32_16x16x32_bf16 v[8:11], v[108:111], v[214:217], v[8:11]
	s_setprio 0
	s_setprio 1
	v_mfma_f32_16x16x32_bf16 v[52:55], v[154:157], v[176:179], v[52:55]
	v_mfma_f32_16x16x32_bf16 v[44:47], v[168:171], v[176:179], v[44:47]
	v_mfma_f32_16x16x32_bf16 v[36:39], v[154:157], v[184:187], v[36:39]
	v_mfma_f32_16x16x32_bf16 v[28:31], v[168:171], v[184:187], v[28:31]
	v_mfma_f32_16x16x32_bf16 v[20:23], v[154:157], v[202:205], v[20:23]
	v_mfma_f32_16x16x32_bf16 v[12:15], v[168:171], v[202:205], v[12:15]
	v_mfma_f32_16x16x32_bf16 v[4:7], v[154:157], v[210:213], v[4:7]
	v_mfma_f32_16x16x32_bf16 v[0:3], v[168:171], v[210:213], v[0:3]
	v_mfma_f32_16x16x32_bf16 v[52:55], v[164:167], v[180:183], v[52:55]
	v_mfma_f32_16x16x32_bf16 v[44:47], v[172:175], v[180:183], v[44:47]
	v_mfma_f32_16x16x32_bf16 v[36:39], v[164:167], v[188:191], v[36:39]
	v_mfma_f32_16x16x32_bf16 v[28:31], v[172:175], v[188:191], v[28:31]
	v_mfma_f32_16x16x32_bf16 v[20:23], v[164:167], v[206:209], v[20:23]
	v_mfma_f32_16x16x32_bf16 v[12:15], v[172:175], v[206:209], v[12:15]
	v_mfma_f32_16x16x32_bf16 v[4:7], v[164:167], v[214:217], v[4:7]
	v_mfma_f32_16x16x32_bf16 v[0:3], v[172:175], v[214:217], v[0:3]
	s_setprio 0
	s_barrier
	s_add_i32 s82, 0, 0x18000
	s_add_i32 s84, 0, 0x1c000
	v_add_u32_e32 v108, s82, v161
	v_add_u32_e32 v172, s84, v161
	ds_read_b128 v[96:99], v108
	ds_read_b128 v[100:103], v108 offset:1024
	ds_read_b128 v[104:107], v108 offset:2048
	ds_read_b128 v[108:111], v108 offset:3072
	ds_read_b128 v[154:157], v172
	ds_read_b128 v[164:167], v172 offset:1024
	ds_read_b128 v[168:171], v172 offset:2048
	ds_read_b128 v[172:175], v172 offset:3072
	s_add_u32 s18, s18, 0x80000
	s_addc_u32 s19, s19, 0
	s_mov_b32 m0, s36
	v_lshl_add_u64 v[222:223], s[18:19], 0, v[148:149]
	ds_read_b128 v[176:179], v163 offset:32768
	ds_read_b128 v[180:183], v163 offset:33792
	ds_read_b128 v[184:187], v163 offset:34816
	ds_read_b128 v[188:191], v163 offset:35840
	ds_read_b128 v[202:205], v163 offset:36864
	ds_read_b128 v[206:209], v163 offset:37888
	ds_read_b128 v[210:213], v163 offset:38912
	ds_read_b128 v[214:217], v163 offset:39936
	global_load_lds_dwordx4 v[222:223], off
	v_lshl_add_u64 v[222:223], s[18:19], 0, v[146:147]
	s_mov_b32 m0, s46
	s_nop 0
	global_load_lds_dwordx4 v[222:223], off
	s_waitcnt vmcnt(8)
	s_waitcnt lgkmcnt(0)
	s_barrier
	s_setprio 1
	s_waitcnt lgkmcnt(0)
	v_mfma_f32_16x16x32_bf16 v[140:143], v[96:99], v[176:179], v[140:143]
	v_mfma_f32_16x16x32_bf16 v[136:139], v[104:107], v[176:179], v[136:139]
	v_mfma_f32_16x16x32_bf16 v[124:127], v[96:99], v[184:187], v[124:127]
	v_mfma_f32_16x16x32_bf16 v[120:123], v[104:107], v[184:187], v[120:123]
	v_mfma_f32_16x16x32_bf16 v[92:95], v[96:99], v[202:205], v[92:95]
	v_mfma_f32_16x16x32_bf16 v[88:91], v[104:107], v[202:205], v[88:91]
	v_mfma_f32_16x16x32_bf16 v[76:79], v[96:99], v[210:213], v[76:79]
	v_mfma_f32_16x16x32_bf16 v[72:75], v[104:107], v[210:213], v[72:75]
	v_mfma_f32_16x16x32_bf16 v[140:143], v[100:103], v[180:183], v[140:143]
	v_mfma_f32_16x16x32_bf16 v[136:139], v[108:111], v[180:183], v[136:139]
	v_mfma_f32_16x16x32_bf16 v[124:127], v[100:103], v[188:191], v[124:127]
	v_mfma_f32_16x16x32_bf16 v[120:123], v[108:111], v[188:191], v[120:123]
	v_mfma_f32_16x16x32_bf16 v[92:95], v[100:103], v[206:209], v[92:95]
	v_mfma_f32_16x16x32_bf16 v[88:91], v[108:111], v[206:209], v[88:91]
	v_mfma_f32_16x16x32_bf16 v[76:79], v[100:103], v[214:217], v[76:79]
	v_mfma_f32_16x16x32_bf16 v[72:75], v[108:111], v[214:217], v[72:75]
	s_setprio 0
	s_setprio 1
	v_mfma_f32_16x16x32_bf16 v[132:135], v[154:157], v[176:179], v[132:135]
	v_mfma_f32_16x16x32_bf16 v[128:131], v[168:171], v[176:179], v[128:131]
	v_mfma_f32_16x16x32_bf16 v[116:119], v[154:157], v[184:187], v[116:119]
	v_mfma_f32_16x16x32_bf16 v[112:115], v[168:171], v[184:187], v[112:115]
	v_mfma_f32_16x16x32_bf16 v[84:87], v[154:157], v[202:205], v[84:87]
	v_mfma_f32_16x16x32_bf16 v[80:83], v[168:171], v[202:205], v[80:83]
	v_mfma_f32_16x16x32_bf16 v[68:71], v[154:157], v[210:213], v[68:71]
	v_mfma_f32_16x16x32_bf16 v[64:67], v[168:171], v[210:213], v[64:67]
	v_mfma_f32_16x16x32_bf16 v[132:135], v[164:167], v[180:183], v[132:135]
	v_mfma_f32_16x16x32_bf16 v[128:131], v[172:175], v[180:183], v[128:131]
	v_mfma_f32_16x16x32_bf16 v[116:119], v[164:167], v[188:191], v[116:119]
	v_mfma_f32_16x16x32_bf16 v[112:115], v[172:175], v[188:191], v[112:115]
	v_mfma_f32_16x16x32_bf16 v[84:87], v[164:167], v[206:209], v[84:87]
	v_mfma_f32_16x16x32_bf16 v[80:83], v[172:175], v[206:209], v[80:83]
	v_mfma_f32_16x16x32_bf16 v[68:71], v[164:167], v[214:217], v[68:71]
	v_mfma_f32_16x16x32_bf16 v[64:67], v[172:175], v[214:217], v[64:67]
	s_setprio 0
	s_barrier
	s_add_i32 s18, s82, s24
	v_lshl_add_u64 v[158:159], v[158:159], 0, s[42:43]
	s_mov_b32 m0, s18
	ds_read_b128 v[176:179], v163 offset:49152
	ds_read_b128 v[180:183], v163 offset:50176
	ds_read_b128 v[184:187], v163 offset:51200
	ds_read_b128 v[188:191], v163 offset:52224
	ds_read_b128 v[202:205], v163 offset:53248
	ds_read_b128 v[206:209], v163 offset:54272
	ds_read_b128 v[210:213], v163 offset:55296
	ds_read_b128 v[214:217], v163 offset:56320
	global_load_lds_dwordx4 v[158:159], off
	s_add_i32 m0, s18, 0x2000
	s_add_u32 s16, s16, 0x80080
	v_lshl_add_u64 v[158:159], v[196:197], 0, s[42:43]
	s_addc_u32 s17, s17, 0
	s_add_i32 s18, s84, s24
	global_load_lds_dwordx4 v[158:159], off
	v_lshl_add_u64 v[158:159], s[16:17], 0, v[192:193]
	s_mov_b32 m0, s18
	s_nop 0
	global_load_lds_dwordx4 v[158:159], off
	v_lshl_add_u64 v[158:159], s[16:17], 0, v[144:145]
	s_add_i32 m0, s18, 0x2000
	s_nop 0
	global_load_lds_dwordx4 v[158:159], off
	v_lshl_add_u64 v[158:159], v[218:219], 0, s[42:43]
	s_mov_b32 m0, s70
	s_nop 0
	global_load_lds_dwordx4 v[158:159], off
	v_lshl_add_u64 v[158:159], v[220:221], 0, s[42:43]
	s_mov_b32 m0, s71
	s_nop 0
	global_load_lds_dwordx4 v[158:159], off
	s_waitcnt vmcnt(8)
	s_waitcnt lgkmcnt(0)
	s_barrier
	s_setprio 1
	s_waitcnt lgkmcnt(0)
	v_mfma_f32_16x16x32_bf16 v[60:63], v[96:99], v[176:179], v[60:63]
	v_mfma_f32_16x16x32_bf16 v[56:59], v[104:107], v[176:179], v[56:59]
	v_mfma_f32_16x16x32_bf16 v[48:51], v[96:99], v[184:187], v[48:51]
	v_mfma_f32_16x16x32_bf16 v[40:43], v[104:107], v[184:187], v[40:43]
	v_mfma_f32_16x16x32_bf16 v[32:35], v[96:99], v[202:205], v[32:35]
	v_mfma_f32_16x16x32_bf16 v[24:27], v[104:107], v[202:205], v[24:27]
	v_mfma_f32_16x16x32_bf16 v[16:19], v[96:99], v[210:213], v[16:19]
	v_mfma_f32_16x16x32_bf16 v[8:11], v[104:107], v[210:213], v[8:11]
	v_mfma_f32_16x16x32_bf16 v[60:63], v[100:103], v[180:183], v[60:63]
	v_mfma_f32_16x16x32_bf16 v[56:59], v[108:111], v[180:183], v[56:59]
	v_mfma_f32_16x16x32_bf16 v[48:51], v[100:103], v[188:191], v[48:51]
	v_mfma_f32_16x16x32_bf16 v[40:43], v[108:111], v[188:191], v[40:43]
	v_mfma_f32_16x16x32_bf16 v[32:35], v[100:103], v[206:209], v[32:35]
	v_mfma_f32_16x16x32_bf16 v[24:27], v[108:111], v[206:209], v[24:27]
	v_mfma_f32_16x16x32_bf16 v[16:19], v[100:103], v[214:217], v[16:19]
	v_mfma_f32_16x16x32_bf16 v[8:11], v[108:111], v[214:217], v[8:11]
	s_setprio 0
	s_setprio 1
	v_mfma_f32_16x16x32_bf16 v[52:55], v[154:157], v[176:179], v[52:55]
	v_mfma_f32_16x16x32_bf16 v[44:47], v[168:171], v[176:179], v[44:47]
	v_mfma_f32_16x16x32_bf16 v[36:39], v[154:157], v[184:187], v[36:39]
	v_mfma_f32_16x16x32_bf16 v[28:31], v[168:171], v[184:187], v[28:31]
	v_mfma_f32_16x16x32_bf16 v[20:23], v[154:157], v[202:205], v[20:23]
	v_mfma_f32_16x16x32_bf16 v[12:15], v[168:171], v[202:205], v[12:15]
	v_mfma_f32_16x16x32_bf16 v[4:7], v[154:157], v[210:213], v[4:7]
	v_mfma_f32_16x16x32_bf16 v[0:3], v[168:171], v[210:213], v[0:3]
	v_mfma_f32_16x16x32_bf16 v[52:55], v[164:167], v[180:183], v[52:55]
	v_mfma_f32_16x16x32_bf16 v[44:47], v[172:175], v[180:183], v[44:47]
	v_mfma_f32_16x16x32_bf16 v[36:39], v[164:167], v[188:191], v[36:39]
	v_mfma_f32_16x16x32_bf16 v[28:31], v[172:175], v[188:191], v[28:31]
	v_mfma_f32_16x16x32_bf16 v[20:23], v[164:167], v[206:209], v[20:23]
	v_mfma_f32_16x16x32_bf16 v[12:15], v[172:175], v[206:209], v[12:15]
	v_mfma_f32_16x16x32_bf16 v[4:7], v[164:167], v[214:217], v[4:7]
	v_mfma_f32_16x16x32_bf16 v[0:3], v[172:175], v[214:217], v[0:3]
	s_add_i32 s80, s80, 2
	s_add_u32 s40, s40, 0x100
	s_addc_u32 s41, s41, 0
	s_add_u32 s52, s52, 0x100
	s_addc_u32 s53, s53, 0
	s_cmp_gt_u32 s80, 29
	s_setprio 0
	s_barrier
	s_cbranch_scc0 .LBB0_109
	s_and_b64 vcc, exec, s[6:7]
	s_cbranch_vccz .LBB0_112
	s_barrier

.LBB0_246:
	s_add_u32 s6, s0, 0xfff80080
	s_addc_u32 s7, s1, -1
	s_add_i32 s80, 0, 0x10000
	s_cmp_eq_u32 s78, 28
	s_cselect_b32 s17, s13, s7
	s_cselect_b32 s16, s70, s6
	s_cselect_b32 s7, s11, s76
	s_cselect_b32 s6, s71, s74
	s_add_i32 s82, 0, 0x14000
	v_add_u32_e32 v152, s80, v167
	v_add_u32_e32 v164, s82, v167
	ds_read_b128 v[140:143], v152
	s_waitcnt lgkmcnt(0)
	ds_read_b128 v[144:147], v152 offset:1024
	ds_read_b128 v[148:151], v152 offset:2048
	ds_read_b128 v[152:155], v152 offset:3072
	ds_read_b128 v[156:159], v164
	ds_read_b128 v[160:163], v164 offset:1024
	ds_read_b128 v[170:173], v164 offset:2048
	ds_read_b128 v[174:177], v164 offset:3072
	v_lshl_add_u64 v[164:165], s[0:1], 0, v[136:137]
	s_add_i32 m0, s26, 0xc000
	ds_read_b128 v[178:181], v169
	ds_read_b128 v[182:185], v169 offset:1024
	ds_read_b128 v[186:189], v169 offset:2048
	ds_read_b128 v[202:205], v169 offset:3072
	ds_read_b128 v[206:209], v169 offset:4096
	ds_read_b128 v[210:213], v169 offset:5120
	ds_read_b128 v[214:217], v169 offset:6144
	ds_read_b128 v[218:221], v169 offset:7168
	global_load_lds_dwordx4 v[164:165], off
	v_lshl_add_u64 v[164:165], s[0:1], 0, v[138:139]
	s_add_i32 m0, s26, 0xe000
	s_nop 0
	global_load_lds_dwordx4 v[164:165], off
	s_waitcnt vmcnt(8)
	s_waitcnt lgkmcnt(0)
	s_barrier
	s_setprio 1
	s_waitcnt lgkmcnt(0)
	v_mfma_f32_16x16x32_bf16 v[124:127], v[140:143], v[178:181], v[124:127]
	v_mfma_f32_16x16x32_bf16 v[120:123], v[148:151], v[178:181], v[120:123]
	v_mfma_f32_16x16x32_bf16 v[108:111], v[140:143], v[186:189], v[108:111]
	v_mfma_f32_16x16x32_bf16 v[104:107], v[148:151], v[186:189], v[104:107]
	v_mfma_f32_16x16x32_bf16 v[92:95], v[140:143], v[206:209], v[92:95]
	v_mfma_f32_16x16x32_bf16 v[88:91], v[148:151], v[206:209], v[88:91]
	v_mfma_f32_16x16x32_bf16 v[76:79], v[140:143], v[214:217], v[76:79]
	v_mfma_f32_16x16x32_bf16 v[72:75], v[148:151], v[214:217], v[72:75]
	v_mfma_f32_16x16x32_bf16 v[124:127], v[144:147], v[182:185], v[124:127]
	v_mfma_f32_16x16x32_bf16 v[120:123], v[152:155], v[182:185], v[120:123]
	v_mfma_f32_16x16x32_bf16 v[108:111], v[144:147], v[202:205], v[108:111]
	v_mfma_f32_16x16x32_bf16 v[104:107], v[152:155], v[202:205], v[104:107]
	v_mfma_f32_16x16x32_bf16 v[92:95], v[144:147], v[210:213], v[92:95]
	v_mfma_f32_16x16x32_bf16 v[88:91], v[152:155], v[210:213], v[88:91]
	v_mfma_f32_16x16x32_bf16 v[76:79], v[144:147], v[218:221], v[76:79]
	v_mfma_f32_16x16x32_bf16 v[72:75], v[152:155], v[218:221], v[72:75]
	s_setprio 0
	s_setprio 1
	v_mfma_f32_16x16x32_bf16 v[116:119], v[156:159], v[178:181], v[116:119]
	v_mfma_f32_16x16x32_bf16 v[112:115], v[170:173], v[178:181], v[112:115]
	v_mfma_f32_16x16x32_bf16 v[100:103], v[156:159], v[186:189], v[100:103]
	v_mfma_f32_16x16x32_bf16 v[96:99], v[170:173], v[186:189], v[96:99]
	v_mfma_f32_16x16x32_bf16 v[84:87], v[156:159], v[206:209], v[84:87]
	v_mfma_f32_16x16x32_bf16 v[80:83], v[170:173], v[206:209], v[80:83]
	v_mfma_f32_16x16x32_bf16 v[68:71], v[156:159], v[214:217], v[68:71]
	v_mfma_f32_16x16x32_bf16 v[64:67], v[170:173], v[214:217], v[64:67]
	v_mfma_f32_16x16x32_bf16 v[116:119], v[160:163], v[182:185], v[116:119]
	v_mfma_f32_16x16x32_bf16 v[112:115], v[174:177], v[182:185], v[112:115]
	v_mfma_f32_16x16x32_bf16 v[100:103], v[160:163], v[202:205], v[100:103]
	v_mfma_f32_16x16x32_bf16 v[96:99], v[174:177], v[202:205], v[96:99]
	v_mfma_f32_16x16x32_bf16 v[84:87], v[160:163], v[210:213], v[84:87]
	v_mfma_f32_16x16x32_bf16 v[80:83], v[174:177], v[210:213], v[80:83]
	v_mfma_f32_16x16x32_bf16 v[68:71], v[160:163], v[218:221], v[68:71]
	v_mfma_f32_16x16x32_bf16 v[64:67], v[174:177], v[218:221], v[64:67]
	s_setprio 0
	s_barrier
	s_add_i32 s80, s80, s20
	v_lshl_add_u64 v[164:165], s[6:7], 0, v[132:133]
	s_mov_b32 m0, s80
	ds_read_b128 v[178:181], v169 offset:16384
	ds_read_b128 v[182:185], v169 offset:17408
	ds_read_b128 v[186:189], v169 offset:18432
	ds_read_b128 v[202:205], v169 offset:19456
	ds_read_b128 v[206:209], v169 offset:20480
	ds_read_b128 v[210:213], v169 offset:21504
	ds_read_b128 v[214:217], v169 offset:22528
	ds_read_b128 v[218:221], v169 offset:23552
	global_load_lds_dwordx4 v[164:165], off
	s_add_i32 m0, s80, 0x2000
	s_add_u32 vcc_lo, s6, 0x80000
	v_lshl_add_u64 v[190:191], s[6:7], 0, v[128:129]
	s_addc_u32 vcc_hi, s7, 0
	s_add_i32 s80, s82, s20
	global_load_lds_dwordx4 v[190:191], off
	v_lshl_add_u64 v[196:197], vcc, 0, v[132:133]
	s_mov_b32 m0, s80
	v_lshl_add_u64 v[222:223], s[16:17], 0, v[130:131]
	global_load_lds_dwordx4 v[196:197], off
	v_lshl_add_u64 v[196:197], vcc, 0, v[128:129]
	s_add_i32 m0, s80, 0x2000
	s_nop 0
	global_load_lds_dwordx4 v[196:197], off
	v_lshl_add_u64 v[196:197], s[16:17], 0, v[134:135]
	s_mov_b32 m0, s26
	s_nop 0
	global_load_lds_dwordx4 v[196:197], off
	s_mov_b32 m0, s28
	s_nop 0
	global_load_lds_dwordx4 v[222:223], off
	s_waitcnt vmcnt(8)
	s_waitcnt lgkmcnt(0)
	s_barrier
	s_setprio 1
	s_waitcnt lgkmcnt(0)
	v_mfma_f32_16x16x32_bf16 v[60:63], v[140:143], v[178:181], v[60:63]
	v_mfma_f32_16x16x32_bf16 v[56:59], v[148:151], v[178:181], v[56:59]
	v_mfma_f32_16x16x32_bf16 v[44:47], v[140:143], v[186:189], v[44:47]
	v_mfma_f32_16x16x32_bf16 v[40:43], v[148:151], v[186:189], v[40:43]
	v_mfma_f32_16x16x32_bf16 v[28:31], v[140:143], v[206:209], v[28:31]
	v_mfma_f32_16x16x32_bf16 v[24:27], v[148:151], v[206:209], v[24:27]
	v_mfma_f32_16x16x32_bf16 v[12:15], v[140:143], v[214:217], v[12:15]
	v_mfma_f32_16x16x32_bf16 v[8:11], v[148:151], v[214:217], v[8:11]
	v_mfma_f32_16x16x32_bf16 v[60:63], v[144:147], v[182:185], v[60:63]
	v_mfma_f32_16x16x32_bf16 v[56:59], v[152:155], v[182:185], v[56:59]
	v_mfma_f32_16x16x32_bf16 v[44:47], v[144:147], v[202:205], v[44:47]
	v_mfma_f32_16x16x32_bf16 v[40:43], v[152:155], v[202:205], v[40:43]
	v_mfma_f32_16x16x32_bf16 v[28:31], v[144:147], v[210:213], v[28:31]
	v_mfma_f32_16x16x32_bf16 v[24:27], v[152:155], v[210:213], v[24:27]
	v_mfma_f32_16x16x32_bf16 v[12:15], v[144:147], v[218:221], v[12:15]
	v_mfma_f32_16x16x32_bf16 v[8:11], v[152:155], v[218:221], v[8:11]
	s_setprio 0
	s_setprio 1
	v_mfma_f32_16x16x32_bf16 v[52:55], v[156:159], v[178:181], v[52:55]
	v_mfma_f32_16x16x32_bf16 v[48:51], v[170:173], v[178:181], v[48:51]
	v_mfma_f32_16x16x32_bf16 v[36:39], v[156:159], v[186:189], v[36:39]
	v_mfma_f32_16x16x32_bf16 v[32:35], v[170:173], v[186:189], v[32:35]
	v_mfma_f32_16x16x32_bf16 v[20:23], v[156:159], v[206:209], v[20:23]
	v_mfma_f32_16x16x32_bf16 v[16:19], v[170:173], v[206:209], v[16:19]
	v_mfma_f32_16x16x32_bf16 v[4:7], v[156:159], v[214:217], v[4:7]
	v_mfma_f32_16x16x32_bf16 v[0:3], v[170:173], v[214:217], v[0:3]
	v_mfma_f32_16x16x32_bf16 v[52:55], v[160:163], v[182:185], v[52:55]
	v_mfma_f32_16x16x32_bf16 v[48:51], v[174:177], v[182:185], v[48:51]
	v_mfma_f32_16x16x32_bf16 v[36:39], v[160:163], v[202:205], v[36:39]
	v_mfma_f32_16x16x32_bf16 v[32:35], v[174:177], v[202:205], v[32:35]
	v_mfma_f32_16x16x32_bf16 v[20:23], v[160:163], v[210:213], v[20:23]
	v_mfma_f32_16x16x32_bf16 v[16:19], v[174:177], v[210:213], v[16:19]
	v_mfma_f32_16x16x32_bf16 v[4:7], v[160:163], v[218:221], v[4:7]
	v_mfma_f32_16x16x32_bf16 v[0:3], v[174:177], v[218:221], v[0:3]
	s_setprio 0
	s_barrier
	s_add_i32 s80, 0, 0x18000
	s_add_i32 s82, 0, 0x1c000
	v_add_u32_e32 v152, s80, v167
	v_add_u32_e32 v174, s82, v167
	ds_read_b128 v[140:143], v152
	ds_read_b128 v[144:147], v152 offset:1024
	ds_read_b128 v[148:151], v152 offset:2048
	ds_read_b128 v[152:155], v152 offset:3072
	ds_read_b128 v[156:159], v174
	ds_read_b128 v[160:163], v174 offset:1024
	ds_read_b128 v[170:173], v174 offset:2048
	ds_read_b128 v[174:177], v174 offset:3072
	s_add_u32 s16, s16, 0x80000
	s_addc_u32 s17, s17, 0
	s_mov_b32 m0, s36
	v_lshl_add_u64 v[246:247], s[16:17], 0, v[134:135]
	ds_read_b128 v[178:181], v169 offset:32768
	ds_read_b128 v[182:185], v169 offset:33792
	ds_read_b128 v[186:189], v169 offset:34816
	ds_read_b128 v[202:205], v169 offset:35840
	ds_read_b128 v[206:209], v169 offset:36864
	ds_read_b128 v[210:213], v169 offset:37888
	ds_read_b128 v[214:217], v169 offset:38912
	ds_read_b128 v[218:221], v169 offset:39936
	global_load_lds_dwordx4 v[246:247], off
	v_lshl_add_u64 v[246:247], s[16:17], 0, v[130:131]
	s_mov_b32 m0, s46
	s_nop 0
	global_load_lds_dwordx4 v[246:247], off
	s_waitcnt vmcnt(8)
	s_waitcnt lgkmcnt(0)
	s_barrier
	s_setprio 1
	s_waitcnt lgkmcnt(0)
	v_mfma_f32_16x16x32_bf16 v[124:127], v[140:143], v[178:181], v[124:127]
	v_mfma_f32_16x16x32_bf16 v[120:123], v[148:151], v[178:181], v[120:123]
	v_mfma_f32_16x16x32_bf16 v[108:111], v[140:143], v[186:189], v[108:111]
	v_mfma_f32_16x16x32_bf16 v[104:107], v[148:151], v[186:189], v[104:107]
	v_mfma_f32_16x16x32_bf16 v[92:95], v[140:143], v[206:209], v[92:95]
	v_mfma_f32_16x16x32_bf16 v[88:91], v[148:151], v[206:209], v[88:91]
	v_mfma_f32_16x16x32_bf16 v[76:79], v[140:143], v[214:217], v[76:79]
	v_mfma_f32_16x16x32_bf16 v[72:75], v[148:151], v[214:217], v[72:75]
	v_mfma_f32_16x16x32_bf16 v[124:127], v[144:147], v[182:185], v[124:127]
	v_mfma_f32_16x16x32_bf16 v[120:123], v[152:155], v[182:185], v[120:123]
	v_mfma_f32_16x16x32_bf16 v[108:111], v[144:147], v[202:205], v[108:111]
	v_mfma_f32_16x16x32_bf16 v[104:107], v[152:155], v[202:205], v[104:107]
	v_mfma_f32_16x16x32_bf16 v[92:95], v[144:147], v[210:213], v[92:95]
	v_mfma_f32_16x16x32_bf16 v[88:91], v[152:155], v[210:213], v[88:91]
	v_mfma_f32_16x16x32_bf16 v[76:79], v[144:147], v[218:221], v[76:79]
	v_mfma_f32_16x16x32_bf16 v[72:75], v[152:155], v[218:221], v[72:75]
	s_setprio 0
	s_setprio 1
	v_mfma_f32_16x16x32_bf16 v[116:119], v[156:159], v[178:181], v[116:119]
	v_mfma_f32_16x16x32_bf16 v[112:115], v[170:173], v[178:181], v[112:115]
	v_mfma_f32_16x16x32_bf16 v[100:103], v[156:159], v[186:189], v[100:103]
	v_mfma_f32_16x16x32_bf16 v[96:99], v[170:173], v[186:189], v[96:99]
	v_mfma_f32_16x16x32_bf16 v[84:87], v[156:159], v[206:209], v[84:87]
	v_mfma_f32_16x16x32_bf16 v[80:83], v[170:173], v[206:209], v[80:83]
	v_mfma_f32_16x16x32_bf16 v[68:71], v[156:159], v[214:217], v[68:71]
	v_mfma_f32_16x16x32_bf16 v[64:67], v[170:173], v[214:217], v[64:67]
	v_mfma_f32_16x16x32_bf16 v[116:119], v[160:163], v[182:185], v[116:119]
	v_mfma_f32_16x16x32_bf16 v[112:115], v[174:177], v[182:185], v[112:115]
	v_mfma_f32_16x16x32_bf16 v[100:103], v[160:163], v[202:205], v[100:103]
	v_mfma_f32_16x16x32_bf16 v[96:99], v[174:177], v[202:205], v[96:99]
	v_mfma_f32_16x16x32_bf16 v[84:87], v[160:163], v[210:213], v[84:87]
	v_mfma_f32_16x16x32_bf16 v[80:83], v[174:177], v[210:213], v[80:83]
	v_mfma_f32_16x16x32_bf16 v[68:71], v[160:163], v[218:221], v[68:71]
	v_mfma_f32_16x16x32_bf16 v[64:67], v[174:177], v[218:221], v[64:67]
	s_setprio 0
	s_barrier
	s_add_i32 s16, s80, s20
	v_lshl_add_u64 v[164:165], v[164:165], 0, s[42:43]
	s_mov_b32 m0, s16
	ds_read_b128 v[178:181], v169 offset:49152
	ds_read_b128 v[182:185], v169 offset:50176
	ds_read_b128 v[186:189], v169 offset:51200
	ds_read_b128 v[202:205], v169 offset:52224
	ds_read_b128 v[206:209], v169 offset:53248
	ds_read_b128 v[210:213], v169 offset:54272
	ds_read_b128 v[214:217], v169 offset:55296
	ds_read_b128 v[218:221], v169 offset:56320
	global_load_lds_dwordx4 v[164:165], off
	s_add_i32 m0, s16, 0x2000
	s_add_u32 s6, s6, 0x80080
	v_lshl_add_u64 v[164:165], v[190:191], 0, s[42:43]
	s_addc_u32 s7, s7, 0
	s_add_i32 s16, s82, s20
	global_load_lds_dwordx4 v[164:165], off
	v_lshl_add_u64 v[164:165], s[6:7], 0, v[132:133]
	s_mov_b32 m0, s16
	s_nop 0
	global_load_lds_dwordx4 v[164:165], off
	v_lshl_add_u64 v[164:165], s[6:7], 0, v[128:129]
	s_add_i32 m0, s16, 0x2000
	s_nop 0
	global_load_lds_dwordx4 v[164:165], off
	v_lshl_add_u64 v[164:165], v[196:197], 0, s[42:43]
	s_mov_b32 m0, s56
	s_nop 0
	global_load_lds_dwordx4 v[164:165], off
	v_lshl_add_u64 v[164:165], v[222:223], 0, s[42:43]
	s_mov_b32 m0, s68
	s_nop 0
	global_load_lds_dwordx4 v[164:165], off
	s_waitcnt vmcnt(8)
	s_waitcnt lgkmcnt(0)
	s_barrier
	s_setprio 1
	s_waitcnt lgkmcnt(0)
	v_mfma_f32_16x16x32_bf16 v[60:63], v[140:143], v[178:181], v[60:63]
	v_mfma_f32_16x16x32_bf16 v[56:59], v[148:151], v[178:181], v[56:59]
	v_mfma_f32_16x16x32_bf16 v[44:47], v[140:143], v[186:189], v[44:47]
	v_mfma_f32_16x16x32_bf16 v[40:43], v[148:151], v[186:189], v[40:43]
	v_mfma_f32_16x16x32_bf16 v[28:31], v[140:143], v[206:209], v[28:31]
	v_mfma_f32_16x16x32_bf16 v[24:27], v[148:151], v[206:209], v[24:27]
	v_mfma_f32_16x16x32_bf16 v[12:15], v[140:143], v[214:217], v[12:15]
	v_mfma_f32_16x16x32_bf16 v[8:11], v[148:151], v[214:217], v[8:11]
	v_mfma_f32_16x16x32_bf16 v[60:63], v[144:147], v[182:185], v[60:63]
	v_mfma_f32_16x16x32_bf16 v[56:59], v[152:155], v[182:185], v[56:59]
	v_mfma_f32_16x16x32_bf16 v[44:47], v[144:147], v[202:205], v[44:47]
	v_mfma_f32_16x16x32_bf16 v[40:43], v[152:155], v[202:205], v[40:43]
	v_mfma_f32_16x16x32_bf16 v[28:31], v[144:147], v[210:213], v[28:31]
	v_mfma_f32_16x16x32_bf16 v[24:27], v[152:155], v[210:213], v[24:27]
	v_mfma_f32_16x16x32_bf16 v[12:15], v[144:147], v[218:221], v[12:15]
	v_mfma_f32_16x16x32_bf16 v[8:11], v[152:155], v[218:221], v[8:11]
	s_setprio 0
	s_setprio 1
	v_mfma_f32_16x16x32_bf16 v[52:55], v[156:159], v[178:181], v[52:55]
	v_mfma_f32_16x16x32_bf16 v[48:51], v[170:173], v[178:181], v[48:51]
	v_mfma_f32_16x16x32_bf16 v[36:39], v[156:159], v[186:189], v[36:39]
	v_mfma_f32_16x16x32_bf16 v[32:35], v[170:173], v[186:189], v[32:35]
	v_mfma_f32_16x16x32_bf16 v[20:23], v[156:159], v[206:209], v[20:23]
	v_mfma_f32_16x16x32_bf16 v[16:19], v[170:173], v[206:209], v[16:19]
	v_mfma_f32_16x16x32_bf16 v[4:7], v[156:159], v[214:217], v[4:7]
	v_mfma_f32_16x16x32_bf16 v[0:3], v[170:173], v[214:217], v[0:3]
	v_mfma_f32_16x16x32_bf16 v[52:55], v[160:163], v[182:185], v[52:55]
	v_mfma_f32_16x16x32_bf16 v[48:51], v[174:177], v[182:185], v[48:51]
	v_mfma_f32_16x16x32_bf16 v[36:39], v[160:163], v[202:205], v[36:39]
	v_mfma_f32_16x16x32_bf16 v[32:35], v[174:177], v[202:205], v[32:35]
	v_mfma_f32_16x16x32_bf16 v[20:23], v[160:163], v[210:213], v[20:23]
	v_mfma_f32_16x16x32_bf16 v[16:19], v[174:177], v[210:213], v[16:19]
	v_mfma_f32_16x16x32_bf16 v[4:7], v[160:163], v[218:221], v[4:7]
	v_mfma_f32_16x16x32_bf16 v[0:3], v[174:177], v[218:221], v[0:3]
	s_add_i32 s78, s78, 2
	s_add_u32 s0, s0, 0x100
	s_addc_u32 s1, s1, 0
	s_add_u32 s74, s74, 0x100
	s_addc_u32 s76, s76, 0
	s_cmp_gt_u32 s78, 29
	s_setprio 0
	s_barrier
	s_cbranch_scc0 .LBB0_246
	s_and_b64 vcc, exec, s[8:9]
	s_cbranch_vccz .LBB0_249
	s_barrier
